# kv up-projection epilogue: per-row partial-sum loads issued ahead of the previous row's stores, vmcnt(2) instead of a full drain
# speedup vs baseline: 1.0133x; 1.0026x over previous
.LBB0_454:
	v_lshl_add_u32 v148, s6, 8, v150
	v_ashrrev_i32_e32 v149, 31, v148
	v_lshlrev_b64 v[146:147], 5, v[148:149]
	v_lshl_add_u64 v[146:147], s[16:17], 0, v[146:147]
	global_load_dwordx4 v[162:165], v[146:147], off
	global_load_dwordx4 v[166:169], v[146:147], off offset:16
	v_lshlrev_b64 v[172:173], 11, v[148:149]
	s_mul_i32 s28, s7, 0xc0
	s_lshl_b32 s6, s7, 7
	v_mov_b64_e32 v[146:147], s[82:83]
	s_ashr_i32 s29, s28, 31
	s_ashr_i32 s7, s6, 31
	v_mad_i64_i32 v[158:159], s[30:31], v148, s47, v[146:147]
	s_lshl_b64 s[30:31], s[28:29], 1
	s_lshl_b64 s[28:29], s[6:7], 1
	v_lshl_add_u64 v[172:173], s[94:95], 0, v[172:173]
	v_or_b32_e32 v170, 16, v148
	v_lshl_add_u64 v[158:159], v[158:159], 0, s[30:31]
	v_lshl_add_u64 v[172:173], v[172:173], 0, s[28:29]
	v_ashrrev_i32_e32 v171, 31, v170
	v_lshl_add_u64 v[158:159], v[158:159], 0, s[0:1]
	v_lshlrev_b64 v[174:175], 5, v[170:171]
	v_lshl_add_u64 v[158:159], v[158:159], 0, v[128:129]
	s_waitcnt vmcnt(0)
	v_mov_b32_e32 v176, v162
	v_mov_b32_e32 v177, v166
	v_mov_b32_e32 v166, v163
	v_mov_b32_e32 v162, v164
	v_mov_b32_e32 v163, v168
	v_mov_b32_e32 v168, v165
	v_pk_add_f32 v[164:165], v[176:177], v[166:167]
	v_pk_add_f32 v[162:163], v[162:163], v[168:169]
	s_nop 0
	v_pk_add_f32 v[162:163], v[164:165], v[162:163]
	v_lshl_add_u64 v[164:165], v[172:173], 0, s[0:1]
	v_add_f32_e32 v149, v162, v163
	v_fmamk_f32 v149, v149, 0x3b000000, v155
	v_mul_f32_e32 v157, 0x4f800000, v149
	v_cmp_gt_f32_e32 vcc, s46, v149
	v_lshl_add_u64 v[164:165], v[164:165], 0, v[128:129]
	v_lshl_add_u64 v[162:163], s[16:17], 0, v[174:175]
	v_cndmask_b32_e32 v149, v149, v157, vcc
	v_sqrt_f32_e32 v157, v149
	s_nop 0
	v_add_u32_e32 v166, -1, v157
	v_add_u32_e32 v167, 1, v157
	v_fma_f32 v168, -v166, v157, v149
	v_fma_f32 v169, -v167, v157, v149
	v_cmp_ge_f32_e64 s[6:7], 0, v168
	s_nop 1
	v_cndmask_b32_e64 v157, v157, v166, s[6:7]
	v_cmp_lt_f32_e64 s[6:7], 0, v169
	s_nop 1
	v_cndmask_b32_e64 v157, v157, v167, s[6:7]
	v_mul_f32_e32 v166, 0x37800000, v157
	v_cndmask_b32_e32 v157, v157, v166, vcc
	v_cmp_class_f32_e32 vcc, v149, v156
	s_nop 1
	v_cndmask_b32_e32 v149, v157, v149, vcc
	v_div_scale_f32 v157, s[6:7], v149, v149, 1.0
	v_rcp_f32_e32 v166, v157
	v_div_scale_f32 v167, vcc, 1.0, v149, 1.0
	v_fma_f32 v168, -v157, v166, 1.0
	v_fmac_f32_e32 v166, v168, v166
	v_mul_f32_e32 v168, v167, v166
	v_fma_f32 v169, -v157, v168, v167
	v_fmac_f32_e32 v168, v169, v166
	v_fma_f32 v157, -v157, v168, v167
	v_div_fmas_f32 v157, v157, v166, v168
	v_div_fixup_f32 v166, v157, v149, 1.0
	v_pk_mul_f32 v[126:127], v[126:127], v[166:167] op_sel_hi:[1,0]
	v_pk_mul_f32 v[124:125], v[124:125], v[166:167] op_sel_hi:[1,0]
	v_pk_mul_f32 v[122:123], v[122:123], v[166:167] op_sel_hi:[1,0]
	v_pk_mul_f32 v[120:121], v[120:121], v[166:167] op_sel_hi:[1,0]
	v_pk_mul_f32 v[118:119], v[118:119], v[166:167] op_sel_hi:[1,0]
	v_pk_mul_f32 v[116:117], v[116:117], v[166:167] op_sel_hi:[1,0]
	v_pk_mul_f32 v[168:169], v[114:115], v[166:167] op_sel_hi:[1,0]
	v_pk_mul_f32 v[166:167], v[112:113], v[166:167] op_sel_hi:[1,0]
	v_cvt_pk_bf16_f32 v112, v124, v125
	v_cvt_pk_bf16_f32 v113, v126, v127
	v_cvt_pk_bf16_f32 v114, v120, v121
	v_cvt_pk_bf16_f32 v115, v122, v123
	global_load_dwordx4 v[248:251], v[162:163], off
	global_load_dwordx4 v[252:255], v[162:163], off offset:16
	global_store_dwordx4 v[158:159], v[112:115], off
	v_mad_i64_i32 v[122:123], s[6:7], v170, s47, v[146:147]
	s_nop 0
	v_cvt_pk_bf16_f32 v112, v116, v117
	v_cvt_pk_bf16_f32 v113, v118, v119
	v_cvt_pk_bf16_f32 v114, v166, v167
	v_cvt_pk_bf16_f32 v115, v168, v169
	global_store_dwordx4 v[164:165], v[112:115], off
	v_lshl_add_u64 v[122:123], v[122:123], 0, s[30:31]
	v_lshl_add_u64 v[122:123], v[122:123], 0, s[0:1]
	v_lshlrev_b64 v[124:125], 11, v[170:171]
	v_lshl_add_u64 v[124:125], s[94:95], 0, v[124:125]
	v_or_b32_e32 v120, 32, v148
	v_ashrrev_i32_e32 v121, 31, v120
	v_lshlrev_b64 v[126:127], 5, v[120:121]
	v_lshl_add_u64 v[126:127], s[16:17], 0, v[126:127]
	s_waitcnt vmcnt(2)
	v_mov_b32_e32 v112, v248
	v_mov_b32_e32 v113, v249
	v_mov_b32_e32 v114, v250
	v_mov_b32_e32 v115, v251
	v_mov_b32_e32 v116, v252
	v_mov_b32_e32 v117, v253
	v_mov_b32_e32 v118, v254
	v_mov_b32_e32 v119, v255
	v_mov_b32_e32 v158, v112
	s_nop 0
	v_mov_b32_e32 v159, v116
	v_mov_b32_e32 v116, v113
	v_mov_b32_e32 v112, v114
	v_mov_b32_e32 v113, v118
	v_mov_b32_e32 v118, v115
	v_pk_add_f32 v[114:115], v[158:159], v[116:117]
	v_pk_add_f32 v[112:113], v[112:113], v[118:119]
	s_nop 0
	v_pk_add_f32 v[112:113], v[114:115], v[112:113]
	v_lshl_add_u64 v[114:115], v[124:125], 0, s[28:29]
	v_add_f32_e32 v112, v112, v113
	v_fmamk_f32 v112, v112, 0x3b000000, v155
	v_mul_f32_e32 v113, 0x4f800000, v112
	v_cmp_gt_f32_e32 vcc, s46, v112
	v_lshl_add_u64 v[114:115], v[114:115], 0, s[0:1]
	v_lshl_add_u64 v[114:115], v[114:115], 0, v[128:129]
	v_cndmask_b32_e32 v116, v112, v113, vcc
	v_sqrt_f32_e32 v117, v116
	v_lshl_add_u64 v[112:113], v[122:123], 0, v[128:129]
	v_add_u32_e32 v118, -1, v117
	v_add_u32_e32 v119, 1, v117
	v_fma_f32 v122, -v118, v117, v116
	v_fma_f32 v123, -v119, v117, v116
	v_cmp_ge_f32_e64 s[6:7], 0, v122
	s_nop 1
	v_cndmask_b32_e64 v117, v117, v118, s[6:7]
	v_cmp_lt_f32_e64 s[6:7], 0, v123
	s_nop 1
	v_cndmask_b32_e64 v117, v117, v119, s[6:7]
	v_mul_f32_e32 v118, 0x37800000, v117
	v_cndmask_b32_e32 v117, v117, v118, vcc
	v_cmp_class_f32_e32 vcc, v116, v156
	s_nop 1
	v_cndmask_b32_e32 v116, v117, v116, vcc
	v_div_scale_f32 v117, s[6:7], v116, v116, 1.0
	v_rcp_f32_e32 v118, v117
	v_div_scale_f32 v119, vcc, 1.0, v116, 1.0
	v_fma_f32 v122, -v117, v118, 1.0
	v_fmac_f32_e32 v118, v122, v118
	v_mul_f32_e32 v122, v119, v118
	v_fma_f32 v123, -v117, v122, v119
	v_fmac_f32_e32 v122, v123, v118
	v_fma_f32 v117, -v117, v122, v119
	v_div_fmas_f32 v117, v117, v118, v122
	v_div_fixup_f32 v116, v117, v116, 1.0
	v_pk_mul_f32 v[110:111], v[110:111], v[116:117] op_sel_hi:[1,0]
	v_pk_mul_f32 v[108:109], v[108:109], v[116:117] op_sel_hi:[1,0]
	v_pk_mul_f32 v[106:107], v[106:107], v[116:117] op_sel_hi:[1,0]
	v_pk_mul_f32 v[104:105], v[104:105], v[116:117] op_sel_hi:[1,0]
	v_pk_mul_f32 v[102:103], v[102:103], v[116:117] op_sel_hi:[1,0]
	v_pk_mul_f32 v[100:101], v[100:101], v[116:117] op_sel_hi:[1,0]
	v_pk_mul_f32 v[118:119], v[98:99], v[116:117] op_sel_hi:[1,0]
	v_pk_mul_f32 v[116:117], v[96:97], v[116:117] op_sel_hi:[1,0]
	v_cvt_pk_bf16_f32 v96, v108, v109
	v_cvt_pk_bf16_f32 v97, v110, v111
	v_cvt_pk_bf16_f32 v98, v104, v105
	v_cvt_pk_bf16_f32 v99, v106, v107
	global_load_dwordx4 v[248:251], v[126:127], off
	global_load_dwordx4 v[252:255], v[126:127], off offset:16
	global_store_dwordx4 v[112:113], v[96:99], off
	v_mad_i64_i32 v[106:107], s[6:7], v120, s47, v[146:147]
	s_nop 0
	v_cvt_pk_bf16_f32 v96, v100, v101
	v_cvt_pk_bf16_f32 v97, v102, v103
	v_cvt_pk_bf16_f32 v98, v116, v117
	v_cvt_pk_bf16_f32 v99, v118, v119
	global_store_dwordx4 v[114:115], v[96:99], off
	v_lshl_add_u64 v[106:107], v[106:107], 0, s[30:31]
	v_lshl_add_u64 v[106:107], v[106:107], 0, s[0:1]
	v_lshlrev_b64 v[108:109], 11, v[120:121]
	v_lshl_add_u64 v[108:109], s[94:95], 0, v[108:109]
	v_or_b32_e32 v104, 48, v148
	v_ashrrev_i32_e32 v105, 31, v104
	v_lshlrev_b64 v[110:111], 5, v[104:105]
	v_lshl_add_u64 v[110:111], s[16:17], 0, v[110:111]
	s_waitcnt vmcnt(2)
	v_mov_b32_e32 v96, v248
	v_mov_b32_e32 v97, v249
	v_mov_b32_e32 v98, v250
	v_mov_b32_e32 v99, v251
	v_mov_b32_e32 v100, v252
	v_mov_b32_e32 v101, v253
	v_mov_b32_e32 v102, v254
	v_mov_b32_e32 v103, v255
	v_mov_b32_e32 v112, v96
	s_nop 0
	v_mov_b32_e32 v113, v100
	v_mov_b32_e32 v100, v97
	v_mov_b32_e32 v96, v98
	v_mov_b32_e32 v97, v102
	v_mov_b32_e32 v102, v99
	v_pk_add_f32 v[98:99], v[112:113], v[100:101]
	v_pk_add_f32 v[96:97], v[96:97], v[102:103]
	s_nop 0
	v_pk_add_f32 v[96:97], v[98:99], v[96:97]
	v_lshl_add_u64 v[98:99], v[108:109], 0, s[28:29]
	v_add_f32_e32 v96, v96, v97
	v_fmamk_f32 v96, v96, 0x3b000000, v155
	v_mul_f32_e32 v97, 0x4f800000, v96
	v_cmp_gt_f32_e32 vcc, s46, v96
	v_lshl_add_u64 v[98:99], v[98:99], 0, s[0:1]
	v_lshl_add_u64 v[98:99], v[98:99], 0, v[128:129]
	v_cndmask_b32_e32 v100, v96, v97, vcc
	v_sqrt_f32_e32 v101, v100
	v_lshl_add_u64 v[96:97], v[106:107], 0, v[128:129]
	v_add_u32_e32 v102, -1, v101
	v_add_u32_e32 v103, 1, v101
	v_fma_f32 v106, -v102, v101, v100
	v_fma_f32 v107, -v103, v101, v100
	v_cmp_ge_f32_e64 s[6:7], 0, v106
	s_nop 1
	v_cndmask_b32_e64 v101, v101, v102, s[6:7]
	v_cmp_lt_f32_e64 s[6:7], 0, v107
	s_nop 1
	v_cndmask_b32_e64 v101, v101, v103, s[6:7]
	v_mul_f32_e32 v102, 0x37800000, v101
	v_cndmask_b32_e32 v101, v101, v102, vcc
	v_cmp_class_f32_e32 vcc, v100, v156
	s_nop 1
	v_cndmask_b32_e32 v100, v101, v100, vcc
	v_div_scale_f32 v101, s[6:7], v100, v100, 1.0
	v_rcp_f32_e32 v102, v101
	v_div_scale_f32 v103, vcc, 1.0, v100, 1.0
	v_fma_f32 v106, -v101, v102, 1.0
	v_fmac_f32_e32 v102, v106, v102
	v_mul_f32_e32 v106, v103, v102
	v_fma_f32 v107, -v101, v106, v103
	v_fmac_f32_e32 v106, v107, v102
	v_fma_f32 v101, -v101, v106, v103
	v_div_fmas_f32 v101, v101, v102, v106
	v_div_fixup_f32 v100, v101, v100, 1.0
	v_pk_mul_f32 v[94:95], v[94:95], v[100:101] op_sel_hi:[1,0]
	v_pk_mul_f32 v[92:93], v[92:93], v[100:101] op_sel_hi:[1,0]
	v_pk_mul_f32 v[90:91], v[90:91], v[100:101] op_sel_hi:[1,0]
	v_pk_mul_f32 v[88:89], v[88:89], v[100:101] op_sel_hi:[1,0]
	v_pk_mul_f32 v[86:87], v[86:87], v[100:101] op_sel_hi:[1,0]
	v_pk_mul_f32 v[84:85], v[84:85], v[100:101] op_sel_hi:[1,0]
	v_pk_mul_f32 v[102:103], v[82:83], v[100:101] op_sel_hi:[1,0]
	v_pk_mul_f32 v[100:101], v[80:81], v[100:101] op_sel_hi:[1,0]
	v_cvt_pk_bf16_f32 v80, v92, v93
	v_cvt_pk_bf16_f32 v81, v94, v95
	v_cvt_pk_bf16_f32 v82, v88, v89
	v_cvt_pk_bf16_f32 v83, v90, v91
	global_load_dwordx4 v[248:251], v[110:111], off
	global_load_dwordx4 v[252:255], v[110:111], off offset:16
	global_store_dwordx4 v[96:97], v[80:83], off
	v_mad_i64_i32 v[90:91], s[6:7], v104, s47, v[146:147]
	s_nop 0
	v_cvt_pk_bf16_f32 v80, v84, v85
	v_cvt_pk_bf16_f32 v81, v86, v87
	v_cvt_pk_bf16_f32 v82, v100, v101
	v_cvt_pk_bf16_f32 v83, v102, v103
	global_store_dwordx4 v[98:99], v[80:83], off
	v_lshl_add_u64 v[90:91], v[90:91], 0, s[30:31]
	v_lshl_add_u64 v[90:91], v[90:91], 0, s[0:1]
	v_lshlrev_b64 v[92:93], 11, v[104:105]
	v_lshl_add_u64 v[92:93], s[94:95], 0, v[92:93]
	v_add_u32_e32 v88, 0x80, v148
	v_ashrrev_i32_e32 v89, 31, v88
	v_lshlrev_b64 v[94:95], 5, v[88:89]
	v_lshl_add_u64 v[94:95], s[16:17], 0, v[94:95]
	s_waitcnt vmcnt(2)
	v_mov_b32_e32 v80, v248
	v_mov_b32_e32 v81, v249
	v_mov_b32_e32 v82, v250
	v_mov_b32_e32 v83, v251
	v_mov_b32_e32 v84, v252
	v_mov_b32_e32 v85, v253
	v_mov_b32_e32 v86, v254
	v_mov_b32_e32 v87, v255
	v_mov_b32_e32 v96, v80
	s_nop 0
	v_mov_b32_e32 v97, v84
	v_mov_b32_e32 v84, v81
	v_mov_b32_e32 v80, v82
	v_mov_b32_e32 v81, v86
	v_mov_b32_e32 v86, v83
	v_pk_add_f32 v[82:83], v[96:97], v[84:85]
	v_pk_add_f32 v[80:81], v[80:81], v[86:87]
	s_nop 0
	v_pk_add_f32 v[80:81], v[82:83], v[80:81]
	v_lshl_add_u64 v[82:83], v[92:93], 0, s[28:29]
	v_add_f32_e32 v80, v80, v81
	v_fmamk_f32 v80, v80, 0x3b000000, v155
	v_mul_f32_e32 v81, 0x4f800000, v80
	v_cmp_gt_f32_e32 vcc, s46, v80
	v_lshl_add_u64 v[82:83], v[82:83], 0, s[0:1]
	v_lshl_add_u64 v[82:83], v[82:83], 0, v[128:129]
	v_cndmask_b32_e32 v84, v80, v81, vcc
	v_sqrt_f32_e32 v85, v84
	v_lshl_add_u64 v[80:81], v[90:91], 0, v[128:129]
	v_add_u32_e32 v86, -1, v85
	v_add_u32_e32 v87, 1, v85
	v_fma_f32 v90, -v86, v85, v84
	v_fma_f32 v91, -v87, v85, v84
	v_cmp_ge_f32_e64 s[6:7], 0, v90
	s_nop 1
	v_cndmask_b32_e64 v85, v85, v86, s[6:7]
	v_cmp_lt_f32_e64 s[6:7], 0, v91
	s_nop 1
	v_cndmask_b32_e64 v85, v85, v87, s[6:7]
	v_mul_f32_e32 v86, 0x37800000, v85
	v_cndmask_b32_e32 v85, v85, v86, vcc
	v_cmp_class_f32_e32 vcc, v84, v156
	s_nop 1
	v_cndmask_b32_e32 v84, v85, v84, vcc
	v_div_scale_f32 v85, s[6:7], v84, v84, 1.0
	v_rcp_f32_e32 v86, v85
	v_div_scale_f32 v87, vcc, 1.0, v84, 1.0
	v_fma_f32 v90, -v85, v86, 1.0
	v_fmac_f32_e32 v86, v90, v86
	v_mul_f32_e32 v90, v87, v86
	v_fma_f32 v91, -v85, v90, v87
	v_fmac_f32_e32 v90, v91, v86
	v_fma_f32 v85, -v85, v90, v87
	v_div_fmas_f32 v85, v85, v86, v90
	v_div_fixup_f32 v84, v85, v84, 1.0
	v_pk_mul_f32 v[78:79], v[78:79], v[84:85] op_sel_hi:[1,0]
	v_pk_mul_f32 v[76:77], v[76:77], v[84:85] op_sel_hi:[1,0]
	v_pk_mul_f32 v[74:75], v[74:75], v[84:85] op_sel_hi:[1,0]
	v_pk_mul_f32 v[72:73], v[72:73], v[84:85] op_sel_hi:[1,0]
	v_pk_mul_f32 v[70:71], v[70:71], v[84:85] op_sel_hi:[1,0]
	v_pk_mul_f32 v[68:69], v[68:69], v[84:85] op_sel_hi:[1,0]
	v_pk_mul_f32 v[86:87], v[66:67], v[84:85] op_sel_hi:[1,0]
	v_pk_mul_f32 v[84:85], v[64:65], v[84:85] op_sel_hi:[1,0]
	v_cvt_pk_bf16_f32 v64, v76, v77
	v_cvt_pk_bf16_f32 v65, v78, v79
	v_cvt_pk_bf16_f32 v66, v72, v73
	v_cvt_pk_bf16_f32 v67, v74, v75
	global_load_dwordx4 v[248:251], v[94:95], off
	global_load_dwordx4 v[252:255], v[94:95], off offset:16
	global_store_dwordx4 v[80:81], v[64:67], off
	v_mad_i64_i32 v[74:75], s[6:7], v88, s47, v[146:147]
	s_nop 0
	v_cvt_pk_bf16_f32 v64, v68, v69
	v_cvt_pk_bf16_f32 v65, v70, v71
	v_cvt_pk_bf16_f32 v66, v84, v85
	v_cvt_pk_bf16_f32 v67, v86, v87
	global_store_dwordx4 v[82:83], v[64:67], off
	v_lshl_add_u64 v[74:75], v[74:75], 0, s[30:31]
	v_lshl_add_u64 v[74:75], v[74:75], 0, s[0:1]
	v_lshlrev_b64 v[76:77], 11, v[88:89]
	v_lshl_add_u64 v[76:77], s[94:95], 0, v[76:77]
	v_add_u32_e32 v72, 0x90, v148
	v_ashrrev_i32_e32 v73, 31, v72
	v_lshlrev_b64 v[78:79], 5, v[72:73]
	v_lshl_add_u64 v[78:79], s[16:17], 0, v[78:79]
	s_waitcnt vmcnt(2)
	v_mov_b32_e32 v64, v248
	v_mov_b32_e32 v65, v249
	v_mov_b32_e32 v66, v250
	v_mov_b32_e32 v67, v251
	v_mov_b32_e32 v68, v252
	v_mov_b32_e32 v69, v253
	v_mov_b32_e32 v70, v254
	v_mov_b32_e32 v71, v255
	v_mov_b32_e32 v80, v64
	s_nop 0
	v_mov_b32_e32 v81, v68
	v_mov_b32_e32 v68, v65
	v_mov_b32_e32 v64, v66
	v_mov_b32_e32 v65, v70
	v_mov_b32_e32 v70, v67
	v_pk_add_f32 v[66:67], v[80:81], v[68:69]
	v_pk_add_f32 v[64:65], v[64:65], v[70:71]
	s_nop 0
	v_pk_add_f32 v[64:65], v[66:67], v[64:65]
	v_lshl_add_u64 v[66:67], v[76:77], 0, s[28:29]
	v_add_f32_e32 v64, v64, v65
	v_fmamk_f32 v64, v64, 0x3b000000, v155
	v_mul_f32_e32 v65, 0x4f800000, v64
	v_cmp_gt_f32_e32 vcc, s46, v64
	v_lshl_add_u64 v[66:67], v[66:67], 0, s[0:1]
	v_lshl_add_u64 v[66:67], v[66:67], 0, v[128:129]
	v_cndmask_b32_e32 v68, v64, v65, vcc
	v_sqrt_f32_e32 v69, v68
	v_lshl_add_u64 v[64:65], v[74:75], 0, v[128:129]
	v_add_u32_e32 v70, -1, v69
	v_add_u32_e32 v71, 1, v69
	v_fma_f32 v74, -v70, v69, v68
	v_fma_f32 v75, -v71, v69, v68
	v_cmp_ge_f32_e64 s[6:7], 0, v74
	s_nop 1
	v_cndmask_b32_e64 v69, v69, v70, s[6:7]
	v_cmp_lt_f32_e64 s[6:7], 0, v75
	s_nop 1
	v_cndmask_b32_e64 v69, v69, v71, s[6:7]
	v_mul_f32_e32 v70, 0x37800000, v69
	v_cndmask_b32_e32 v69, v69, v70, vcc
	v_cmp_class_f32_e32 vcc, v68, v156
	s_nop 1
	v_cndmask_b32_e32 v68, v69, v68, vcc
	v_div_scale_f32 v69, s[6:7], v68, v68, 1.0
	v_rcp_f32_e32 v70, v69
	v_div_scale_f32 v71, vcc, 1.0, v68, 1.0
	v_fma_f32 v74, -v69, v70, 1.0
	v_fmac_f32_e32 v70, v74, v70
	v_mul_f32_e32 v74, v71, v70
	v_fma_f32 v75, -v69, v74, v71
	v_fmac_f32_e32 v74, v75, v70
	v_fma_f32 v69, -v69, v74, v71
	v_div_fmas_f32 v69, v69, v70, v74
	v_div_fixup_f32 v68, v69, v68, 1.0
	v_pk_mul_f32 v[62:63], v[62:63], v[68:69] op_sel_hi:[1,0]
	v_pk_mul_f32 v[60:61], v[60:61], v[68:69] op_sel_hi:[1,0]
	v_pk_mul_f32 v[58:59], v[58:59], v[68:69] op_sel_hi:[1,0]
	v_pk_mul_f32 v[56:57], v[56:57], v[68:69] op_sel_hi:[1,0]
	v_pk_mul_f32 v[54:55], v[54:55], v[68:69] op_sel_hi:[1,0]
	v_pk_mul_f32 v[52:53], v[52:53], v[68:69] op_sel_hi:[1,0]
	v_pk_mul_f32 v[70:71], v[50:51], v[68:69] op_sel_hi:[1,0]
	v_pk_mul_f32 v[68:69], v[48:49], v[68:69] op_sel_hi:[1,0]
	v_cvt_pk_bf16_f32 v48, v60, v61
	v_cvt_pk_bf16_f32 v49, v62, v63
	v_cvt_pk_bf16_f32 v50, v56, v57
	v_cvt_pk_bf16_f32 v51, v58, v59
	global_load_dwordx4 v[248:251], v[78:79], off
	global_load_dwordx4 v[252:255], v[78:79], off offset:16
	global_store_dwordx4 v[64:65], v[48:51], off
	v_mad_i64_i32 v[58:59], s[6:7], v72, s47, v[146:147]
	s_nop 0
	v_cvt_pk_bf16_f32 v48, v52, v53
	v_cvt_pk_bf16_f32 v49, v54, v55
	v_cvt_pk_bf16_f32 v50, v68, v69
	v_cvt_pk_bf16_f32 v51, v70, v71
	global_store_dwordx4 v[66:67], v[48:51], off
	v_lshl_add_u64 v[58:59], v[58:59], 0, s[30:31]
	v_lshl_add_u64 v[58:59], v[58:59], 0, s[0:1]
	v_lshlrev_b64 v[60:61], 11, v[72:73]
	v_lshl_add_u64 v[60:61], s[94:95], 0, v[60:61]
	v_add_u32_e32 v56, 0xa0, v148
	v_ashrrev_i32_e32 v57, 31, v56
	v_lshlrev_b64 v[62:63], 5, v[56:57]
	v_lshl_add_u64 v[62:63], s[16:17], 0, v[62:63]
	s_waitcnt vmcnt(2)
	v_mov_b32_e32 v48, v248
	v_mov_b32_e32 v49, v249
	v_mov_b32_e32 v50, v250
	v_mov_b32_e32 v51, v251
	v_mov_b32_e32 v52, v252
	v_mov_b32_e32 v53, v253
	v_mov_b32_e32 v54, v254
	v_mov_b32_e32 v55, v255
	v_mov_b32_e32 v64, v48
	s_nop 0
	v_mov_b32_e32 v65, v52
	v_mov_b32_e32 v52, v49
	v_mov_b32_e32 v48, v50
	v_mov_b32_e32 v49, v54
	v_mov_b32_e32 v54, v51
	v_pk_add_f32 v[50:51], v[64:65], v[52:53]
	v_pk_add_f32 v[48:49], v[48:49], v[54:55]
	s_nop 0
	v_pk_add_f32 v[48:49], v[50:51], v[48:49]
	v_lshl_add_u64 v[50:51], v[60:61], 0, s[28:29]
	v_add_f32_e32 v48, v48, v49
	v_fmamk_f32 v48, v48, 0x3b000000, v155
	v_mul_f32_e32 v49, 0x4f800000, v48
	v_cmp_gt_f32_e32 vcc, s46, v48
	v_lshl_add_u64 v[50:51], v[50:51], 0, s[0:1]
	v_lshl_add_u64 v[50:51], v[50:51], 0, v[128:129]
	v_cndmask_b32_e32 v52, v48, v49, vcc
	v_sqrt_f32_e32 v53, v52
	v_lshl_add_u64 v[48:49], v[58:59], 0, v[128:129]
	v_add_u32_e32 v54, -1, v53
	v_add_u32_e32 v55, 1, v53
	v_fma_f32 v58, -v54, v53, v52
	v_fma_f32 v59, -v55, v53, v52
	v_cmp_ge_f32_e64 s[6:7], 0, v58
	s_nop 1
	v_cndmask_b32_e64 v53, v53, v54, s[6:7]
	v_cmp_lt_f32_e64 s[6:7], 0, v59
	s_nop 1
	v_cndmask_b32_e64 v53, v53, v55, s[6:7]
	v_mul_f32_e32 v54, 0x37800000, v53
	v_cndmask_b32_e32 v53, v53, v54, vcc
	v_cmp_class_f32_e32 vcc, v52, v156
	s_nop 1
	v_cndmask_b32_e32 v52, v53, v52, vcc
	v_div_scale_f32 v53, s[6:7], v52, v52, 1.0
	v_rcp_f32_e32 v54, v53
	v_div_scale_f32 v55, vcc, 1.0, v52, 1.0
	v_fma_f32 v58, -v53, v54, 1.0
	v_fmac_f32_e32 v54, v58, v54
	v_mul_f32_e32 v58, v55, v54
	v_fma_f32 v59, -v53, v58, v55
	v_fmac_f32_e32 v58, v59, v54
	v_fma_f32 v53, -v53, v58, v55
	v_div_fmas_f32 v53, v53, v54, v58
	v_div_fixup_f32 v52, v53, v52, 1.0
	v_pk_mul_f32 v[46:47], v[46:47], v[52:53] op_sel_hi:[1,0]
	v_pk_mul_f32 v[44:45], v[44:45], v[52:53] op_sel_hi:[1,0]
	v_pk_mul_f32 v[42:43], v[42:43], v[52:53] op_sel_hi:[1,0]
	v_pk_mul_f32 v[40:41], v[40:41], v[52:53] op_sel_hi:[1,0]
	v_pk_mul_f32 v[38:39], v[38:39], v[52:53] op_sel_hi:[1,0]
	v_pk_mul_f32 v[36:37], v[36:37], v[52:53] op_sel_hi:[1,0]
	v_pk_mul_f32 v[54:55], v[34:35], v[52:53] op_sel_hi:[1,0]
	v_pk_mul_f32 v[52:53], v[32:33], v[52:53] op_sel_hi:[1,0]
	v_cvt_pk_bf16_f32 v32, v44, v45
	v_cvt_pk_bf16_f32 v33, v46, v47
	v_cvt_pk_bf16_f32 v34, v40, v41
	v_cvt_pk_bf16_f32 v35, v42, v43
	global_load_dwordx4 v[248:251], v[62:63], off
	global_load_dwordx4 v[252:255], v[62:63], off offset:16
	global_store_dwordx4 v[48:49], v[32:35], off
	v_mad_i64_i32 v[42:43], s[6:7], v56, s47, v[146:147]
	s_nop 0
	v_cvt_pk_bf16_f32 v32, v36, v37
	v_cvt_pk_bf16_f32 v33, v38, v39
	v_cvt_pk_bf16_f32 v34, v52, v53
	v_cvt_pk_bf16_f32 v35, v54, v55
	global_store_dwordx4 v[50:51], v[32:35], off
	v_lshl_add_u64 v[42:43], v[42:43], 0, s[30:31]
	v_lshl_add_u64 v[42:43], v[42:43], 0, s[0:1]
	v_lshlrev_b64 v[44:45], 11, v[56:57]
	v_lshl_add_u64 v[44:45], s[94:95], 0, v[44:45]
	v_add_u32_e32 v40, 0xb0, v148
	v_ashrrev_i32_e32 v41, 31, v40
	v_lshlrev_b64 v[46:47], 5, v[40:41]
	v_lshl_add_u64 v[46:47], s[16:17], 0, v[46:47]
	s_waitcnt vmcnt(2)
	v_mov_b32_e32 v32, v248
	v_mov_b32_e32 v33, v249
	v_mov_b32_e32 v34, v250
	v_mov_b32_e32 v35, v251
	v_mov_b32_e32 v36, v252
	v_mov_b32_e32 v37, v253
	v_mov_b32_e32 v38, v254
	v_mov_b32_e32 v39, v255
	v_mov_b32_e32 v48, v32
	s_nop 0
	v_mov_b32_e32 v49, v36
	v_mov_b32_e32 v36, v33
	v_mov_b32_e32 v32, v34
	v_mov_b32_e32 v33, v38
	v_mov_b32_e32 v38, v35
	v_pk_add_f32 v[34:35], v[48:49], v[36:37]
	v_pk_add_f32 v[32:33], v[32:33], v[38:39]
	s_nop 0
	v_pk_add_f32 v[32:33], v[34:35], v[32:33]
	v_lshl_add_u64 v[34:35], v[44:45], 0, s[28:29]
	v_add_f32_e32 v32, v32, v33
	v_fmamk_f32 v32, v32, 0x3b000000, v155
	v_mul_f32_e32 v33, 0x4f800000, v32
	v_cmp_gt_f32_e32 vcc, s46, v32
	v_lshl_add_u64 v[34:35], v[34:35], 0, s[0:1]
	v_lshl_add_u64 v[34:35], v[34:35], 0, v[128:129]
	v_cndmask_b32_e32 v36, v32, v33, vcc
	v_sqrt_f32_e32 v37, v36
	v_lshl_add_u64 v[32:33], v[42:43], 0, v[128:129]
	v_add_u32_e32 v38, -1, v37
	v_add_u32_e32 v39, 1, v37
	v_fma_f32 v42, -v38, v37, v36
	v_fma_f32 v43, -v39, v37, v36
	v_cmp_ge_f32_e64 s[6:7], 0, v42
	s_nop 1
	v_cndmask_b32_e64 v37, v37, v38, s[6:7]
	v_cmp_lt_f32_e64 s[6:7], 0, v43
	s_nop 1
	v_cndmask_b32_e64 v37, v37, v39, s[6:7]
	v_mul_f32_e32 v38, 0x37800000, v37
	v_cndmask_b32_e32 v37, v37, v38, vcc
	v_cmp_class_f32_e32 vcc, v36, v156
	s_nop 1
	v_cndmask_b32_e32 v36, v37, v36, vcc
	v_div_scale_f32 v37, s[6:7], v36, v36, 1.0
	v_rcp_f32_e32 v38, v37
	v_div_scale_f32 v39, vcc, 1.0, v36, 1.0
	v_fma_f32 v42, -v37, v38, 1.0
	v_fmac_f32_e32 v38, v42, v38
	v_mul_f32_e32 v42, v39, v38
	v_fma_f32 v43, -v37, v42, v39
	v_fmac_f32_e32 v42, v43, v38
	v_fma_f32 v37, -v37, v42, v39
	v_div_fmas_f32 v37, v37, v38, v42
	v_div_fixup_f32 v36, v37, v36, 1.0
	v_pk_mul_f32 v[30:31], v[30:31], v[36:37] op_sel_hi:[1,0]
	v_pk_mul_f32 v[28:29], v[28:29], v[36:37] op_sel_hi:[1,0]
	v_pk_mul_f32 v[26:27], v[26:27], v[36:37] op_sel_hi:[1,0]
	v_pk_mul_f32 v[24:25], v[24:25], v[36:37] op_sel_hi:[1,0]
	v_pk_mul_f32 v[22:23], v[22:23], v[36:37] op_sel_hi:[1,0]
	v_pk_mul_f32 v[20:21], v[20:21], v[36:37] op_sel_hi:[1,0]
	v_pk_mul_f32 v[38:39], v[18:19], v[36:37] op_sel_hi:[1,0]
	v_pk_mul_f32 v[36:37], v[16:17], v[36:37] op_sel_hi:[1,0]
	v_cvt_pk_bf16_f32 v16, v28, v29
	v_cvt_pk_bf16_f32 v17, v30, v31
	v_cvt_pk_bf16_f32 v18, v24, v25
	v_cvt_pk_bf16_f32 v19, v26, v27
	global_load_dwordx4 v[248:251], v[46:47], off
	global_load_dwordx4 v[252:255], v[46:47], off offset:16
	global_store_dwordx4 v[32:33], v[16:19], off
	v_mad_i64_i32 v[24:25], s[6:7], v40, s47, v[146:147]
	s_nop 0
	v_cvt_pk_bf16_f32 v16, v20, v21
	v_cvt_pk_bf16_f32 v17, v22, v23
	v_cvt_pk_bf16_f32 v18, v36, v37
	v_cvt_pk_bf16_f32 v19, v38, v39
	global_store_dwordx4 v[34:35], v[16:19], off
	v_lshl_add_u64 v[24:25], v[24:25], 0, s[30:31]
	v_lshl_add_u64 v[24:25], v[24:25], 0, s[0:1]
	v_lshlrev_b64 v[26:27], 11, v[40:41]
	v_lshl_add_u64 v[26:27], s[94:95], 0, v[26:27]
	s_waitcnt vmcnt(2)
	v_mov_b32_e32 v16, v248
	v_mov_b32_e32 v17, v249
	v_mov_b32_e32 v18, v250
	v_mov_b32_e32 v19, v251
	v_mov_b32_e32 v20, v252
	v_mov_b32_e32 v21, v253
	v_mov_b32_e32 v22, v254
	v_mov_b32_e32 v23, v255
	v_mov_b32_e32 v28, v16
	s_nop 0
	v_mov_b32_e32 v29, v20
	v_mov_b32_e32 v20, v17
	v_mov_b32_e32 v16, v18
	v_mov_b32_e32 v17, v22
	v_mov_b32_e32 v22, v19
	v_pk_add_f32 v[18:19], v[28:29], v[20:21]
	v_pk_add_f32 v[16:17], v[16:17], v[22:23]
	s_nop 0
	v_pk_add_f32 v[16:17], v[18:19], v[16:17]
	v_lshl_add_u64 v[18:19], v[26:27], 0, s[28:29]
	v_add_f32_e32 v16, v16, v17
	v_fmamk_f32 v16, v16, 0x3b000000, v155
	v_mul_f32_e32 v17, 0x4f800000, v16
	v_cmp_gt_f32_e32 vcc, s46, v16
	v_lshl_add_u64 v[18:19], v[18:19], 0, s[0:1]
	v_lshl_add_u64 v[18:19], v[18:19], 0, v[128:129]
	v_cndmask_b32_e32 v20, v16, v17, vcc
	v_sqrt_f32_e32 v21, v20
	v_lshl_add_u64 v[16:17], v[24:25], 0, v[128:129]
	v_add_u32_e32 v22, -1, v21
	v_add_u32_e32 v23, 1, v21
	v_fma_f32 v24, -v22, v21, v20
	v_fma_f32 v25, -v23, v21, v20
	v_cmp_ge_f32_e64 s[6:7], 0, v24
	s_nop 1
	v_cndmask_b32_e64 v21, v21, v22, s[6:7]
	v_cmp_lt_f32_e64 s[6:7], 0, v25
	s_nop 1
	v_cndmask_b32_e64 v21, v21, v23, s[6:7]
	v_mul_f32_e32 v22, 0x37800000, v21
	v_cndmask_b32_e32 v21, v21, v22, vcc
	v_cmp_class_f32_e32 vcc, v20, v156
	s_nop 1
	v_cndmask_b32_e32 v20, v21, v20, vcc
	v_div_scale_f32 v21, s[6:7], v20, v20, 1.0
	v_rcp_f32_e32 v22, v21
	v_div_scale_f32 v23, vcc, 1.0, v20, 1.0
	v_fma_f32 v24, -v21, v22, 1.0
	v_fmac_f32_e32 v22, v24, v22
	v_mul_f32_e32 v24, v23, v22
	v_fma_f32 v25, -v21, v24, v23
	v_fmac_f32_e32 v24, v25, v22
	v_fma_f32 v21, -v21, v24, v23
	v_div_fmas_f32 v21, v21, v22, v24
	v_div_fixup_f32 v20, v21, v20, 1.0
	s_andn2_b64 vcc, exec, s[4:5]
	v_pk_mul_f32 v[14:15], v[14:15], v[20:21] op_sel_hi:[1,0]
	v_pk_mul_f32 v[12:13], v[12:13], v[20:21] op_sel_hi:[1,0]
	v_pk_mul_f32 v[10:11], v[10:11], v[20:21] op_sel_hi:[1,0]
	v_pk_mul_f32 v[8:9], v[8:9], v[20:21] op_sel_hi:[1,0]
	v_pk_mul_f32 v[6:7], v[6:7], v[20:21] op_sel_hi:[1,0]
	v_pk_mul_f32 v[4:5], v[4:5], v[20:21] op_sel_hi:[1,0]
	v_pk_mul_f32 v[22:23], v[2:3], v[20:21] op_sel_hi:[1,0]
	v_pk_mul_f32 v[20:21], v[0:1], v[20:21] op_sel_hi:[1,0]
	v_cvt_pk_bf16_f32 v0, v12, v13
	v_cvt_pk_bf16_f32 v1, v14, v15
	v_cvt_pk_bf16_f32 v2, v8, v9
	v_cvt_pk_bf16_f32 v3, v10, v11
	s_mov_b64 s[4:5], -1
	global_store_dwordx4 v[16:17], v[0:3], off
	s_nop 1
	v_cvt_pk_bf16_f32 v0, v4, v5
	v_cvt_pk_bf16_f32 v1, v6, v7
	v_cvt_pk_bf16_f32 v2, v20, v21
	v_cvt_pk_bf16_f32 v3, v22, v23
	global_store_dwordx4 v[18:19], v[0:3], off
	s_cbranch_vccnz .LBB0_443
	s_andn2_b64 vcc, exec, s[2:3]
	s_cbranch_vccnz .LBB0_442
	s_barrier
	s_branch .LBB0_442
